# LRU gate stage: all 8 conv-tile LDS reads issued up front behind the A-fragment reads (fresh registers), one wait at first use instead of a wait per read
# speedup vs baseline: 1.0265x; 1.0055x over previous
.LBB0_932:
	s_waitcnt lgkmcnt(0)
	ds_read_b128 v[98:101], v170
	ds_read_b128 v[102:105], v170 offset:16
	ds_read_b128 v[166:169], v170 offset:128
	ds_read_b128 v[178:181], v170 offset:144
	ds_read2_b32 v[182:183], v109 offset1:16
	ds_read2_b32 v[226:227], v109 offset0:64 offset1:80
	ds_read2_b32 v[228:229], v109 offset0:128 offset1:144
	ds_read2_b32 v[230:231], v109 offset0:192 offset1:208
	ds_read2_b32 v[232:233], v109 offset0:32 offset1:48
	ds_read2_b32 v[234:235], v109 offset0:96 offset1:112
	ds_read2_b32 v[236:237], v109 offset0:160 offset1:176
	ds_read2_b32 v[238:239], v109 offset0:224 offset1:240
	s_waitcnt lgkmcnt(11)
	v_cvt_pk_bf16_f32 v162, v98, v99
	v_cvt_pk_bf16_f32 v163, v100, v101
	s_waitcnt lgkmcnt(10)
	v_cvt_pk_bf16_f32 v164, v102, v103
	v_cvt_pk_bf16_f32 v165, v104, v105
	s_waitcnt lgkmcnt(9)
	v_cvt_pk_bf16_f32 v166, v166, v167
	v_cvt_pk_bf16_f32 v167, v168, v169
	s_waitcnt lgkmcnt(8)
	v_cvt_pk_bf16_f32 v168, v178, v179
	v_cvt_pk_bf16_f32 v169, v180, v181
	v_mfma_f32_16x16x32_bf16 v[98:101], v[162:165], v[6:9], v[66:69]
	s_nop 0
	v_mfma_f32_16x16x32_bf16 v[178:181], v[166:169], v[2:5], v[98:101]
	v_mfma_f32_16x16x32_bf16 v[190:193], v[162:165], v[34:37], v[82:85]
	v_mfma_f32_16x16x32_bf16 v[190:193], v[166:169], v[38:41], v[190:193]
	s_nop 5
	v_mul_f32_e32 v98, 0xbfb8aa3b, v178
	v_exp_f32_e32 v98, v98
	v_mfma_f32_16x16x32_bf16 v[102:105], v[162:165], v[10:13], v[70:73]
	v_add_f32_e32 v98, 1.0, v98
	v_rcp_f32_e32 v98, v98
	v_mul_f32_e32 v99, 0xbfb8aa3b, v190
	v_exp_f32_e32 v99, v99
	v_mfma_f32_16x16x32_bf16 v[194:197], v[166:169], v[14:17], v[102:105]
	v_mul_f32_e32 v98, v121, v98
	v_exp_f32_e32 v145, v98
	v_add_f32_e32 v98, 1.0, v99
	v_mul_f32_e32 v102, 0xbfb8aa3b, v179
	v_rcp_f32_e32 v103, v98
	v_fma_f32 v104, -v145, v145, 1.0 clamp
	s_nop 0
	v_exp_f32_e32 v178, v102
	v_sqrt_f32_e32 v104, v104
	s_waitcnt lgkmcnt(0)
	v_mul_f32_e32 v102, v103, v182
	v_mul_f32_e32 v182, 0xbfb8aa3b, v191
	v_add_f32_e32 v178, 1.0, v178
	v_mul_f32_e32 v179, v104, v102
	v_mfma_f32_16x16x32_bf16 v[102:105], v[162:165], v[42:45], v[86:89]
	v_rcp_f32_e32 v178, v178
	v_exp_f32_e32 v182, v182
	v_mul_f32_e32 v190, 0xbfb8aa3b, v195
	v_mfma_f32_16x16x32_bf16 v[198:201], v[166:169], v[46:49], v[102:105]
	v_exp_f32_e32 v190, v190
	v_add_f32_e32 v182, 1.0, v182
	v_rcp_f32_e32 v182, v182
	s_nop 0
	v_mul_f32_e32 v102, v121, v178
	v_exp_f32_e32 v178, v102
	v_mfma_f32_16x16x32_bf16 v[102:105], v[162:165], v[50:53], v[94:97]
	v_fma_f32 v185, -v178, v178, 1.0 clamp
	v_mfma_f32_16x16x32_bf16 v[202:205], v[166:169], v[54:57], v[102:105]
	s_nop 0
	s_nop 4
	v_mul_f32_e32 v102, 0xbfb8aa3b, v180
	v_mfma_f32_16x16x32_bf16 v[186:189], v[162:165], v[18:21], v[74:77]
	v_exp_f32_e32 v180, v102
	v_mfma_f32_16x16x32_bf16 v[98:101], v[162:165], v[26:29], v[78:81]
	v_mfma_f32_16x16x32_bf16 v[102:105], v[162:165], v[58:61], v[90:93]
	v_sqrt_f32_e32 v164, v185
	v_add_f32_e32 v165, 1.0, v180
	v_mfma_f32_16x16x32_bf16 v[186:189], v[166:169], v[22:25], v[186:189]
	v_rcp_f32_e32 v165, v165
	s_nop 0
	v_mul_f32_e32 v162, v182, v226
	v_mul_f32_e32 v162, v164, v162
	v_mfma_f32_16x16x32_bf16 v[98:101], v[166:169], v[30:33], v[98:101]
	v_mul_f32_e32 v165, v121, v165
	v_mul_f32_e32 v182, 0xbfb8aa3b, v194
	v_exp_f32_e32 v182, v182
	v_mfma_f32_16x16x32_bf16 v[102:105], v[166:169], v[62:65], v[102:105]
	v_mul_f32_e32 v166, 0xbfb8aa3b, v192
	v_exp_f32_e32 v166, v166
	v_exp_f32_e32 v168, v165
	s_nop 0
	v_mul_f32_e32 v98, 0xbfb8aa3b, v98
	v_exp_f32_e32 v98, v98
	v_add_f32_e32 v164, 1.0, v166
	v_rcp_f32_e32 v166, v164
	v_mul_f32_e32 v164, 0xbfb8aa3b, v181
	v_exp_f32_e32 v169, v164
	v_fma_f32 v167, -v168, v168, 1.0 clamp
	s_nop 0
	v_sqrt_f32_e32 v167, v167
	v_add_f32_e32 v169, 1.0, v169
	v_mul_f32_e32 v164, v166, v228
	v_mul_f32_e32 v166, 0xbfb8aa3b, v193
	v_exp_f32_e32 v166, v166
	v_rcp_f32_e32 v169, v169
	v_mul_f32_e32 v164, v167, v164
	v_add_f32_e32 v98, 1.0, v98
	v_add_f32_e32 v166, 1.0, v166
	v_rcp_f32_e32 v180, v166
	v_mul_f32_e32 v169, v121, v169
	v_exp_f32_e32 v169, v169
	v_rcp_f32_e32 v98, v98
	v_mul_f32_e32 v102, 0xbfb8aa3b, v102
	v_mul_f32_e32 v166, v180, v230
	v_add_f32_e32 v180, 1.0, v182
	v_fma_f32 v181, -v169, v169, 1.0 clamp
	v_rcp_f32_e32 v180, v180
	v_mul_f32_e32 v182, 0xbfb8aa3b, v198
	v_sqrt_f32_e32 v181, v181
	v_exp_f32_e32 v182, v182
	v_mul_f32_e32 v180, v120, v180
	v_exp_f32_e32 v180, v180
	v_mul_f32_e32 v166, v181, v166
	v_add_f32_e32 v181, 1.0, v182
	v_rcp_f32_e32 v181, v181
	v_fma_f32 v185, -v180, v180, 1.0 clamp
	v_add_u32_e32 v182, 0x1000, v109
	v_sqrt_f32_e32 v185, v185
	ds_write2_b32 v182, v145, v180 offset1:16
	v_mul_f32_e32 v145, v181, v183
	v_mul_f32_e32 v183, 0xbfb8aa3b, v199
	v_exp_f32_e32 v183, v183
	v_add_f32_e32 v180, 1.0, v190
	v_mul_f32_e32 v145, v185, v145
	v_rcp_f32_e32 v180, v180
	v_add_u32_e32 v181, 0x2000, v109
	ds_write2_b32 v181, v179, v145 offset1:16
	v_add_f32_e32 v145, 1.0, v183
	v_mul_f32_e32 v179, 0xbfb8aa3b, v196
	v_rcp_f32_e32 v145, v145
	v_exp_f32_e32 v179, v179
	v_mul_f32_e32 v180, v120, v180
	v_exp_f32_e32 v180, v180
	v_mul_f32_e32 v145, v145, v227
	v_add_f32_e32 v163, 1.0, v179
	v_rcp_f32_e32 v163, v163
	ds_write2_b32 v182, v178, v180 offset0:64 offset1:80
	v_fma_f32 v178, -v180, v180, 1.0 clamp
	v_sqrt_f32_e32 v178, v178
	v_mul_f32_e32 v163, v120, v163
	v_exp_f32_e32 v163, v163
	v_mul_f32_e32 v98, v122, v98
	v_mul_f32_e32 v145, v178, v145
	v_mul_f32_e32 v178, 0xbfb8aa3b, v200
	v_exp_f32_e32 v178, v178
	ds_write2_b32 v181, v162, v145 offset0:64 offset1:80
	ds_write2_b32 v182, v168, v163 offset0:128 offset1:144
	v_fma_f32 v162, -v163, v163, 1.0 clamp
	v_mul_f32_e32 v163, 0xbfb8aa3b, v197
	v_exp_f32_e32 v163, v163
	v_add_f32_e32 v145, 1.0, v178
	v_rcp_f32_e32 v145, v145
	v_add_f32_e32 v163, 1.0, v163
	v_sqrt_f32_e32 v162, v162
	v_rcp_f32_e32 v163, v163
	v_mul_f32_e32 v145, v145, v229
	v_exp_f32_e32 v102, v102
	v_mul_f32_e32 v145, v162, v145
	v_mul_f32_e32 v162, 0xbfb8aa3b, v201
	v_mul_f32_e32 v163, v120, v163
	v_exp_f32_e32 v162, v162
	v_exp_f32_e32 v163, v163
	ds_write2_b32 v181, v164, v145 offset0:128 offset1:144
	v_exp_f32_e32 v98, v98
	v_add_f32_e32 v145, 1.0, v162
	ds_write2_b32 v182, v169, v163 offset0:192 offset1:208
	v_fma_f32 v162, -v163, v163, 1.0 clamp
	v_mul_f32_e32 v163, 0xbfb8aa3b, v186
	v_rcp_f32_e32 v145, v145
	v_exp_f32_e32 v163, v163
	v_sqrt_f32_e32 v162, v162
	v_mul_f32_e32 v145, v145, v231
	v_add_f32_e32 v163, 1.0, v163
	v_rcp_f32_e32 v163, v163
	v_mul_f32_e32 v145, v162, v145
	v_mul_f32_e32 v162, 0xbfb8aa3b, v202
	v_exp_f32_e32 v162, v162
	v_mul_f32_e32 v163, v123, v163
	v_exp_f32_e32 v178, v163
	ds_write2_b32 v181, v166, v145 offset0:192 offset1:208
	v_add_f32_e32 v145, 1.0, v162
	v_mul_f32_e32 v162, 0xbfb8aa3b, v187
	v_mul_f32_e32 v99, 0xbfb8aa3b, v99
	v_exp_f32_e32 v165, v162
	v_exp_f32_e32 v99, v99
	v_add_f32_e32 v102, 1.0, v102
	ds_write2_b32 v182, v178, v98 offset0:32 offset1:48
	v_fma_f32 v98, -v98, v98, 1.0 clamp
	v_add_f32_e32 v165, 1.0, v165
	v_rcp_f32_e32 v102, v102
	v_add_f32_e32 v99, 1.0, v99
	v_rcp_f32_e32 v165, v165
	v_sqrt_f32_e32 v98, v98
	v_rcp_f32_e32 v99, v99
	v_fma_f32 v164, -v178, v178, 1.0 clamp
	v_rcp_f32_e32 v145, v145
	v_mul_f32_e32 v102, v102, v233
	v_sqrt_f32_e32 v164, v164
	v_mul_f32_e32 v165, v123, v165
	v_mul_f32_e32 v98, v98, v102
	v_mul_f32_e32 v102, 0xbfb8aa3b, v103
	v_mul_f32_e32 v99, v122, v99
	v_exp_f32_e32 v179, v165
	v_exp_f32_e32 v102, v102
	v_exp_f32_e32 v99, v99
	v_mul_f32_e32 v145, v145, v232
	v_mul_f32_e32 v162, 0xbfb8aa3b, v203
	v_mul_f32_e32 v145, v164, v145
	v_mul_f32_e32 v164, 0xbfb8aa3b, v188
	v_exp_f32_e32 v162, v162
	v_exp_f32_e32 v167, v164
	ds_write2_b32 v181, v145, v98 offset0:32 offset1:48
	v_add_f32_e32 v98, 1.0, v102
	ds_write2_b32 v182, v179, v99 offset0:96 offset1:112
	v_fma_f32 v99, -v99, v99, 1.0 clamp
	v_rcp_f32_e32 v98, v98
	v_sqrt_f32_e32 v99, v99
	v_add_f32_e32 v162, 1.0, v162
	v_fma_f32 v166, -v179, v179, 1.0 clamp
	v_rcp_f32_e32 v162, v162
	v_mul_f32_e32 v100, 0xbfb8aa3b, v100
	v_mul_f32_e32 v98, v98, v235
	v_sqrt_f32_e32 v166, v166
	v_exp_f32_e32 v100, v100
	v_mul_f32_e32 v98, v99, v98
	v_mul_f32_e32 v99, 0xbfb8aa3b, v104
	v_exp_f32_e32 v99, v99
	v_mul_f32_e32 v162, v162, v234
	v_add_f32_e32 v167, 1.0, v167
	v_mul_f32_e32 v162, v166, v162
	v_add_f32_e32 v100, 1.0, v100
	v_rcp_f32_e32 v167, v167
	v_mul_f32_e32 v164, 0xbfb8aa3b, v204
	v_mul_f32_e32 v166, 0xbfb8aa3b, v189
	v_rcp_f32_e32 v100, v100
	ds_write2_b32 v181, v162, v98 offset0:96 offset1:112
	v_add_f32_e32 v98, 1.0, v99
	v_mul_f32_e32 v99, 0xbfb8aa3b, v101
	v_exp_f32_e32 v164, v164
	v_exp_f32_e32 v169, v166
	v_exp_f32_e32 v99, v99
	v_mul_f32_e32 v167, v123, v167
	v_mul_f32_e32 v100, v122, v100
	v_exp_f32_e32 v180, v167
	v_add_f32_e32 v164, 1.0, v164
	v_add_f32_e32 v169, 1.0, v169
	v_exp_f32_e32 v100, v100
	v_add_f32_e32 v99, 1.0, v99
	v_rcp_f32_e32 v164, v164
	v_rcp_f32_e32 v169, v169
	v_rcp_f32_e32 v99, v99
	v_fma_f32 v168, -v180, v180, 1.0 clamp
	ds_write2_b32 v182, v180, v100 offset0:160 offset1:176
	v_fma_f32 v100, -v100, v100, 1.0 clamp
	v_mul_f32_e32 v164, v164, v236
	v_mul_f32_e32 v166, 0xbfb8aa3b, v205
	v_mul_f32_e32 v169, v123, v169
	v_rcp_f32_e32 v98, v98
	v_mul_f32_e32 v101, 0xbfb8aa3b, v105
	v_mul_f32_e32 v99, v122, v99
	v_sqrt_f32_e32 v168, v168
	v_exp_f32_e32 v166, v166
	v_exp_f32_e32 v183, v169
	v_sqrt_f32_e32 v100, v100
	v_exp_f32_e32 v101, v101
	v_exp_f32_e32 v99, v99
	v_mul_f32_e32 v98, v98, v237
	v_mul_f32_e32 v164, v168, v164
	v_add_f32_e32 v166, 1.0, v166
	v_fma_f32 v185, -v183, v183, 1.0 clamp
	v_mul_f32_e32 v98, v100, v98
	v_add_f32_e32 v100, 1.0, v101
	v_fma_f32 v101, -v99, v99, 1.0 clamp
	v_rcp_f32_e32 v166, v166
	v_rcp_f32_e32 v100, v100
	v_sqrt_f32_e32 v185, v185
	v_sqrt_f32_e32 v101, v101
	v_mul_f32_e32 v166, v166, v238
	ds_write2_b32 v181, v164, v98 offset0:160 offset1:176
	ds_write2_b32 v182, v183, v99 offset0:224 offset1:240
	v_mul_f32_e32 v98, v100, v239
	v_mul_f32_e32 v166, v185, v166
	v_mul_f32_e32 v98, v101, v98
	ds_write2_b32 v181, v166, v98 offset0:224 offset1:240
	s_waitcnt lgkmcnt(0)
	ds_read2st64_b32 v[98:99], v1 offset0:32 offset1:33
	ds_read2st64_b32 v[100:101], v1 offset0:16 offset1:17
	ds_read2st64_b32 v[102:103], v1 offset0:18 offset1:19
	ds_read2st64_b32 v[104:105], v1 offset0:20 offset1:21
	ds_read2st64_b32 v[162:163], v1 offset0:22 offset1:23
	ds_read2st64_b32 v[164:165], v1 offset0:34 offset1:35
	ds_read2st64_b32 v[166:167], v1 offset0:36 offset1:37
	ds_read2st64_b32 v[168:169], v1 offset0:38 offset1:39
	s_waitcnt lgkmcnt(6)
	v_fma_f32 v98, 0, v100, v98
	v_fmac_f32_e32 v99, v98, v101
	s_waitcnt lgkmcnt(2)
	v_fma_f32 v98, v99, v102, v164
	v_fmac_f32_e32 v165, v98, v103
	s_waitcnt lgkmcnt(1)
	v_fma_f32 v98, v165, v104, v166
	v_fmac_f32_e32 v167, v98, v105
	s_waitcnt lgkmcnt(0)
	v_fma_f32 v98, v167, v162, v168
	v_fmac_f32_e32 v169, v98, v163
	ds_read2st64_b32 v[98:99], v1 offset0:40 offset1:41
	ds_read2st64_b32 v[164:165], v1 offset0:24 offset1:25
	ds_read2st64_b32 v[166:167], v1 offset0:26 offset1:27
	ds_read2st64_b32 v[178:179], v1 offset0:28 offset1:29
	ds_read2st64_b32 v[180:181], v1 offset0:30 offset1:31
	ds_read2st64_b32 v[182:183], v1 offset0:42 offset1:43
	ds_read2st64_b32 v[186:187], v1 offset0:44 offset1:45
	ds_read2st64_b32 v[188:189], v1 offset0:46 offset1:47
	v_mul_f32_e32 v101, v100, v101
	v_mul_f32_e32 v101, v101, v102
	v_mul_f32_e32 v101, v101, v103
	v_mul_f32_e32 v101, v101, v104
	v_mul_f32_e32 v101, v101, v105
	v_mul_f32_e32 v101, v101, v162
	v_mul_f32_e32 v101, v101, v163
	s_waitcnt lgkmcnt(6)
	v_fmac_f32_e32 v98, v169, v164
	v_mul_f32_e32 v101, v101, v164
	v_fmac_f32_e32 v99, v98, v165
	v_mul_f32_e32 v101, v101, v165
	s_waitcnt lgkmcnt(2)
	v_fmac_f32_e32 v182, v99, v166
	v_mul_f32_e32 v101, v101, v166
	v_fmac_f32_e32 v183, v182, v167
	v_mul_f32_e32 v101, v101, v167
	s_waitcnt lgkmcnt(1)
	v_fmac_f32_e32 v186, v183, v178
	v_mul_f32_e32 v101, v101, v178
	v_fmac_f32_e32 v187, v186, v179
	v_mul_f32_e32 v101, v101, v179
	s_waitcnt lgkmcnt(0)
	v_fmac_f32_e32 v188, v187, v180
	v_mul_f32_e32 v101, v101, v180
	v_fmac_f32_e32 v189, v188, v181
	v_mul_f32_e32 v101, v101, v181
	v_mov_b32_e32 v98, v189
	s_branch .LBB0_934
